# ph_prep rotary loop: next trip's K/Q row loads issued one trip ahead into spare registers
# speedup vs baseline: 1.0376x; 1.0050x over previous
; __device__ __forceinline__ void ph_prep(bf16_t* Z, const bf16_t* WUQ, const bf16_t* WUKV, const bf16_t* D64, const float* qkq, const float* qkk,
;                                         bf16_t* Q, bf16_t* Kb, bf16_t* Vb, bf16_t* F1lat, bf16_t* F1ctx, unsigned char* lds_) { PH_IDS;
;     ...
; #pragma unroll 1
;         for (int it = tid_; it < 72 * 16; it += NT) {
;             const int row = row0 + (it >> 4), h = (it >> 2) & 3, jg = it & 3;
;             bf16_t* zq = Z + (size_t)row * ZW + C_RQ + h * 64 + 8 * jg; bf16_t* zk = Z + (size_t)row * ZW + C_RK + h * 64 + 8 * jg;
;             const fa::u32x4 k1 = *(const fa::u32x4*)zk, k2 = *(const fa::u32x4*)(zk + 32);
;             f32x4 ka, kb, kc, kd; unpack8(k1, ka, kb); unpack8(k2, kc, kd);
;             if (row < RL) {
;                 const fa::u32x4 q1 = *(const fa::u32x4*)zq, q2 = *(const fa::u32x4*)(zq + 32);
.LBB0_603:
	s_and_saveexec_b64 s[8:9], s[6:7]
	s_cbranch_execz .LBB0_406
	s_mov_b64 s[10:11], 0
	v_mov_b32_e32 v46, v160
	v_mov_b32_e32 v47, v159
	v_mov_b32_e32 v48, v99
	v_mov_b32_e32 v224, v99
	v_ashrrev_i32_e32 v224, 4, v224
	v_add_u32_e32 v224, s57, v224
	v_ashrrev_i32_e32 v225, 31, v224
	v_lshlrev_b64 v[222:223], 12, v[224:225]
	v_lshl_add_u64 v[222:223], s[20:21], 0, v[222:223]
	v_mov_b32_e32 v224, v160
	v_and_b32_e32 v224, 0xc0, v224
	v_lshlrev_b32_e32 v224, 1, v224
	v_mov_b32_e32 v225, 0
	v_lshl_add_u64 v[222:223], v[222:223], 0, v[224:225]
	v_mov_b32_e32 v224, v159
	v_and_b32_e32 v224, 24, v224
	v_lshlrev_b32_e32 v224, 1, v224
	v_lshl_add_u64 v[222:223], v[222:223], 0, v[224:225]
	global_load_dwordx4 v[198:201], v[222:223], off offset:896
	global_load_dwordx4 v[202:205], v[222:223], off offset:832
	global_load_dwordx4 v[206:209], v[222:223], off offset:2944
	global_load_dwordx4 v[210:213], v[222:223], off offset:2880
	s_waitcnt vmcnt(0)
	s_branch .LBB0_606

; __device__ __forceinline__ void ph_prep(bf16_t* Z, const bf16_t* WUQ, const bf16_t* WUKV, const bf16_t* D64, const float* qkq, const float* qkk,
;                                         bf16_t* Q, bf16_t* Kb, bf16_t* Vb, bf16_t* F1lat, bf16_t* F1ctx, unsigned char* lds_) { PH_IDS;
;     ...
;         for (int it = tid_; it < 72 * 16; it += NT) {
;             const int row = row0 + (it >> 4), h = (it >> 2) & 3, jg = it & 3;
;             bf16_t* zq = Z + (size_t)row * ZW + C_RQ + h * 64 + 8 * jg; bf16_t* zk = Z + (size_t)row * ZW + C_RK + h * 64 + 8 * jg;
;             const fa::u32x4 k1 = *(const fa::u32x4*)zk, k2 = *(const fa::u32x4*)(zk + 32);
;             f32x4 ka, kb, kc, kd; unpack8(k1, ka, kb); unpack8(k2, kc, kd);
;             if (row < RL) {
;                 const fa::u32x4 q1 = *(const fa::u32x4*)zq, q2 = *(const fa::u32x4*)(zq + 32);
;                 f32x4 qa, qb, qc, qd; unpack8(q1, qa, qb); unpack8(q2, qc, qd);
;                 const float tpos = (float)(row & 2047);
;                 float x1q[8] = {qa[0], qa[1], qa[2], qa[3], qb[0], qb[1], qb[2], qb[3]}, x2q[8] = {qc[0], qc[1], qc[2], qc[3], qd[0], qd[1], qd[2], qd[3]};
;                 float x1k[8] = {ka[0], ka[1], ka[2], ka[3], kb[0], kb[1], kb[2], kb[3]}, x2k[8] = {kc[0], kc[1], kc[2], kc[3], kd[0], kd[1], kd[2], kd[3]};
; #pragma unroll
;                 for (int e = 0; e < 8; ++e) {
;                     float rev = tpos * (__builtin_amdgcn_exp2f(-(float)(8 * jg + e) * (13.287712379549449f / 32.f)) * 0.15915494309189535f); rev -= floorf(rev);
;                     const float cs = __builtin_amdgcn_cosf(rev), sn = __builtin_amdgcn_sinf(rev);
;                     const float a = x1q[e], c = x2q[e]; x1q[e] = a * cs - c * sn; x2q[e] = a * sn + c * cs;
;                     const float a2 = x1k[e], c2 = x2k[e]; x1k[e] = (a2 * cs - c2 * sn) * 0.125f; x2k[e] = (a2 * sn + c2 * cs) * 0.125f;
;                 }
.LBB0_606:
	v_ashrrev_i32_e32 v18, 4, v48
	v_add_u32_e32 v44, s57, v18
	v_ashrrev_i32_e32 v45, 31, v44
	v_lshlrev_b64 v[18:19], 12, v[44:45]
	v_and_b32_e32 v20, 0xc0, v46
	v_lshl_add_u64 v[18:19], s[20:21], 0, v[18:19]
	v_and_b32_e32 v45, 24, v47
	v_lshlrev_b32_e32 v100, 1, v20
	v_lshl_add_u64 v[18:19], v[18:19], 0, v[100:101]
	v_lshlrev_b32_e32 v100, 1, v45
	v_lshl_add_u64 v[26:27], v[18:19], 0, v[100:101]
	s_waitcnt vmcnt(2)
	v_mov_b32_e32 v18, v198
	v_mov_b32_e32 v19, v199
	v_mov_b32_e32 v20, v200
	v_mov_b32_e32 v21, v201
	v_mov_b32_e32 v22, v202
	v_mov_b32_e32 v23, v203
	v_mov_b32_e32 v24, v204
	v_mov_b32_e32 v25, v205
	v_mov_b32_e32 v214, v206
	v_mov_b32_e32 v215, v207
	v_mov_b32_e32 v216, v208
	v_mov_b32_e32 v217, v209
	v_mov_b32_e32 v218, v210
	v_mov_b32_e32 v219, v211
	v_mov_b32_e32 v220, v212
	v_mov_b32_e32 v221, v213
	v_cmp_ge_i32_e32 vcc, s56, v48
	s_and_saveexec_b64 s[98:99], vcc
	s_cbranch_execz .Lrot_skip_r0
	v_add_u32_e32 v224, 0x200, v48
	v_ashrrev_i32_e32 v224, 4, v224
	v_add_u32_e32 v224, s57, v224
	v_ashrrev_i32_e32 v225, 31, v224
	v_lshlrev_b64 v[222:223], 12, v[224:225]
	v_lshl_add_u64 v[222:223], s[20:21], 0, v[222:223]
	v_add_u32_e32 v224, 0x2000, v46
	v_and_b32_e32 v224, 0xc0, v224
	v_lshlrev_b32_e32 v224, 1, v224
	v_mov_b32_e32 v225, 0
	v_lshl_add_u64 v[222:223], v[222:223], 0, v[224:225]
	v_add_u32_e32 v224, 0x1000, v47
	v_and_b32_e32 v224, 24, v224
	v_lshlrev_b32_e32 v224, 1, v224
	v_lshl_add_u64 v[222:223], v[222:223], 0, v[224:225]
	global_load_dwordx4 v[198:201], v[222:223], off offset:896
	global_load_dwordx4 v[202:205], v[222:223], off offset:832
	global_load_dwordx4 v[206:209], v[222:223], off offset:2944
	global_load_dwordx4 v[210:213], v[222:223], off offset:2880
.Lrot_skip_r0:
	s_mov_b64 exec, s[98:99]
	v_cmp_lt_i32_e32 vcc, s55, v44
	v_lshlrev_b32_e32 v43, 16, v18
	v_lshlrev_b32_e32 v42, 16, v22
	v_and_b32_e32 v39, 0xffff0000, v18
	v_and_b32_e32 v38, 0xffff0000, v22
	v_lshlrev_b32_e32 v41, 16, v19
	v_lshlrev_b32_e32 v40, 16, v23
	v_and_b32_e32 v37, 0xffff0000, v19
	v_and_b32_e32 v36, 0xffff0000, v23
	v_lshlrev_b32_e32 v35, 16, v20
	v_lshlrev_b32_e32 v34, 16, v24
	v_and_b32_e32 v33, 0xffff0000, v20
	v_and_b32_e32 v32, 0xffff0000, v24
	v_lshlrev_b32_e32 v31, 16, v21
	v_lshlrev_b32_e32 v30, 16, v25
	v_and_b32_e32 v29, 0xffff0000, v21
	v_and_b32_e32 v28, 0xffff0000, v25
	s_and_saveexec_b64 s[12:13], vcc
	s_xor_b64 s[12:13], exec, s[12:13]
	s_cbranch_execz .LBB0_608
	v_mov_b32_e32 v18, v40
	v_mov_b32_e32 v19, v36
	v_pk_mul_f32 v[20:21], v[18:19], s[28:29] op_sel_hi:[1,0]
	v_mov_b32_e32 v18, v42
	v_mov_b32_e32 v19, v38
	v_pk_mul_f32 v[18:19], v[18:19], s[28:29] op_sel_hi:[1,0]
	v_mov_b32_e32 v22, v30
	v_mov_b32_e32 v23, v28
	v_mov_b32_e32 v24, v34
	v_mov_b32_e32 v25, v32
	v_pk_mul_f32 v[22:23], v[22:23], s[28:29] op_sel_hi:[1,0]
	v_pk_mul_f32 v[24:25], v[24:25], s[28:29] op_sel_hi:[1,0]
	v_cvt_pk_bf16_f32 v18, v18, v19
	v_cvt_pk_bf16_f32 v19, v20, v21
	v_mov_b32_e32 v36, v41
	v_cvt_pk_bf16_f32 v20, v24, v25
	v_cvt_pk_bf16_f32 v21, v22, v23
	v_mov_b32_e32 v38, v43
	global_store_dwordx4 v[26:27], v[18:21], off offset:832
	v_mov_b32_e32 v28, v31
	v_mov_b32_e32 v32, v35
	v_pk_mul_f32 v[20:21], v[36:37], s[28:29] op_sel_hi:[1,0]
	v_pk_mul_f32 v[18:19], v[38:39], s[28:29] op_sel_hi:[1,0]
	v_pk_mul_f32 v[22:23], v[28:29], s[28:29] op_sel_hi:[1,0]
	v_pk_mul_f32 v[24:25], v[32:33], s[28:29] op_sel_hi:[1,0]
	v_cvt_pk_bf16_f32 v18, v18, v19
	v_cvt_pk_bf16_f32 v19, v20, v21
	s_nop 0
	v_cvt_pk_bf16_f32 v20, v24, v25
	v_cvt_pk_bf16_f32 v21, v22, v23
.LBB0_608:
	s_andn2_saveexec_b64 s[12:13], s[12:13]
	s_cbranch_execz .LBB0_605
	v_mov_b32_e32 v22, v214
	v_mov_b32_e32 v23, v215
	v_mov_b32_e32 v24, v216
	v_mov_b32_e32 v25, v217
	v_mov_b32_e32 v18, v218
	v_mov_b32_e32 v19, v219
	v_mov_b32_e32 v20, v220
	v_mov_b32_e32 v21, v221
	v_cvt_f32_ubyte0_e32 v49, v45
	v_or_b32_e32 v50, 1, v45
	v_or_b32_e32 v51, 2, v45
	v_or_b32_e32 v52, 3, v45
	v_mul_f32_e32 v49, 0xbed49a78, v49
	v_cvt_f32_ubyte0_e32 v50, v50
	v_and_b32_e32 v44, 0x7ff, v44
	v_cvt_f32_ubyte0_e32 v51, v51
	v_cvt_f32_ubyte0_e32 v52, v52
	v_exp_f32_e32 v49, v49
	v_mul_f32_e32 v50, 0xbed49a78, v50
	v_cvt_f32_u32_e32 v44, v44
	v_mul_f32_e32 v51, 0xbed49a78, v51
	v_mul_f32_e32 v52, 0xbed49a78, v52
	v_exp_f32_e32 v50, v50
	v_exp_f32_e32 v51, v51
	v_exp_f32_e32 v52, v52
	v_mul_f32_e32 v49, 0.15915494, v49
	v_mul_f32_e32 v53, v49, v44
	v_mul_f32_e32 v54, 0.15915494, v50
	v_mul_f32_e32 v55, 0.15915494, v51
	v_mul_f32_e32 v52, 0.15915494, v52
	v_floor_f32_e32 v50, v53
	v_mul_f32_e32 v51, v54, v44
	v_mul_f32_e32 v53, v55, v44
	v_mul_f32_e32 v56, v52, v44
	v_fma_f32 v49, v49, v44, -v50
	v_floor_f32_e32 v57, v51
	v_floor_f32_e32 v53, v53
	v_floor_f32_e32 v56, v56
	v_cos_f32_e32 v50, v49
	v_sin_f32_e32 v51, v49
	v_fma_f32 v49, v54, v44, -v57
	v_fma_f32 v55, v55, v44, -v53
	v_fma_f32 v57, v52, v44, -v56
	v_cos_f32_e32 v52, v49
	v_sin_f32_e32 v53, v49
	v_cos_f32_e32 v54, v55
	v_sin_f32_e32 v55, v55
	v_pk_mul_f32 v[60:61], v[50:51], v[42:43]
	v_cos_f32_e32 v56, v57
	v_mov_b32_e32 v58, v51
	v_mov_b32_e32 v59, v50
	v_sub_f32_e32 v49, v60, v61
	v_mov_b32_e32 v60, v53
	v_mov_b32_e32 v61, v52
	v_sin_f32_e32 v57, v57
	v_pk_mul_f32 v[42:43], v[58:59], v[42:43]
	v_pk_mul_f32 v[62:63], v[52:53], v[38:39]
	v_mov_b32_e32 v64, v55
	v_mov_b32_e32 v65, v54
	v_pk_mul_f32 v[38:39], v[60:61], v[38:39]
	v_pk_mul_f32 v[66:67], v[54:55], v[40:41]
; __device__ __forceinline__ pg8::u32x4 pack8(const f32x4 a, const f32x4 b) { pg8::u32x4 w; w.x = pg8::cvt_pk_bf16(a[0], a[1]); w.y = pg8::cvt_pk_bf16(a[2], a[3]); w.z = pg8::cvt_pk_bf16(b[0], b[1]); w.w = pg8::cvt_pk_bf16(b[2], b[3]); return w; }
; __device__ __forceinline__ void ph_prep(bf16_t* Z, const bf16_t* WUQ, const bf16_t* WUKV, const bf16_t* D64, const float* qkq, const float* qkk,
;                                         bf16_t* Q, bf16_t* Kb, bf16_t* Vb, bf16_t* F1lat, bf16_t* F1ctx, unsigned char* lds_) { PH_IDS;
;     ...
; #pragma unroll
;                 for (int e = 0; e < 8; ++e) {
;                     float rev = tpos * (__builtin_amdgcn_exp2f(-(float)(8 * jg + e) * (13.287712379549449f / 32.f)) * 0.15915494309189535f); rev -= floorf(rev);
;                     const float cs = __builtin_amdgcn_cosf(rev), sn = __builtin_amdgcn_sinf(rev);
;                     const float a = x1q[e], c = x2q[e]; x1q[e] = a * cs - c * sn; x2q[e] = a * sn + c * cs;
;                     const float a2 = x1k[e], c2 = x2k[e]; x1k[e] = (a2 * cs - c2 * sn) * 0.125f; x2k[e] = (a2 * sn + c2 * cs) * 0.125f;
;                 }
;                 *(fa::u32x4*)zq = pack8((f32x4){x1q[0], x1q[1], x1q[2], x1q[3]}, (f32x4){x1q[4], x1q[5], x1q[6], x1q[7]});
;                 *(fa::u32x4*)(zq + 32) = pack8((f32x4){x2q[0], x2q[1], x2q[2], x2q[3]}, (f32x4){x2q[4], x2q[5], x2q[6], x2q[7]});
;                 *(fa::u32x4*)zk = pack8((f32x4){x1k[0], x1k[1], x1k[2], x1k[3]}, (f32x4){x1k[4], x1k[5], x1k[6], x1k[7]});
;                 *(fa::u32x4*)(zk + 32) = pack8((f32x4){x2k[0], x2k[1], x2k[2], x2k[3]}, (f32x4){x2k[4], x2k[5], x2k[6], x2k[7]});
	v_add_f32_e32 v42, v42, v43
	v_sub_f32_e32 v43, v62, v63
	v_pk_mul_f32 v[40:41], v[64:65], v[40:41]
	v_add_f32_e32 v38, v38, v39
	v_sub_f32_e32 v62, v66, v67
	v_mul_f32_e32 v66, 0x3e000000, v43
	v_add_f32_e32 v67, v40, v41
	v_mul_f32_e32 v68, 0x3e000000, v38
	v_mul_f32_e32 v63, 0x3e000000, v42
	v_mul_f32_e32 v49, 0x3e000000, v49
	v_mul_f32_e32 v62, 0x3e000000, v62
	v_lshlrev_b32_e32 v39, 16, v22
	v_lshlrev_b32_e32 v38, 16, v18
	v_and_b32_e32 v41, 0xffff0000, v22
	v_lshlrev_b32_e32 v43, 16, v23
	v_and_b32_e32 v23, 0xffff0000, v23
	v_and_b32_e32 v22, 0xffff0000, v19
	v_and_b32_e32 v40, 0xffff0000, v18
	v_lshlrev_b32_e32 v42, 16, v19
	v_pk_mul_f32 v[50:51], v[50:51], v[38:39]
	v_pk_mul_f32 v[18:19], v[56:57], v[22:23]
	v_sub_f32_e32 v50, v50, v51
	v_sub_f32_e32 v51, v18, v19
	v_mov_b32_e32 v18, v57
	v_mov_b32_e32 v19, v56
	v_pk_mul_f32 v[38:39], v[58:59], v[38:39]
	v_pk_mul_f32 v[52:53], v[52:53], v[40:41]
	v_pk_mul_f32 v[22:23], v[18:19], v[22:23]
	v_add_f32_e32 v38, v38, v39
	v_sub_f32_e32 v39, v52, v53
	v_add_f32_e32 v52, v22, v23
	v_pk_mul_f32 v[22:23], v[56:57], v[36:37]
	v_pk_mul_f32 v[18:19], v[18:19], v[36:37]
	v_sub_f32_e32 v22, v22, v23
	v_or_b32_e32 v23, 4, v45
	v_cvt_f32_ubyte0_e32 v23, v23
	v_mul_f32_e32 v23, 0xbed49a78, v23
	v_exp_f32_e32 v23, v23
	v_mul_f32_e32 v53, 0x3e000000, v22
	v_add_f32_e32 v22, v18, v19
	v_pk_mul_f32 v[40:41], v[60:61], v[40:41]
	v_mul_f32_e32 v18, 0.15915494, v23
	v_mul_f32_e32 v19, v18, v44
	v_floor_f32_e32 v19, v19
	v_fma_f32 v19, v18, v44, -v19
	v_cos_f32_e32 v18, v19
	v_sin_f32_e32 v19, v19
	v_pk_mul_f32 v[54:55], v[54:55], v[42:43]
	v_add_f32_e32 v40, v40, v41
	v_sub_f32_e32 v41, v54, v55
	v_mul_f32_e32 v54, 0x3e000000, v22
	v_lshlrev_b32_e32 v23, 16, v24
	v_lshlrev_b32_e32 v22, 16, v20
	v_pk_mul_f32 v[36:37], v[18:19], v[22:23]
	v_pk_mul_f32 v[42:43], v[64:65], v[42:43]
	v_sub_f32_e32 v55, v36, v37
	v_mov_b32_e32 v36, v19
	v_mov_b32_e32 v37, v18
	v_pk_mul_f32 v[18:19], v[18:19], v[34:35]
	v_pk_mul_f32 v[22:23], v[36:37], v[22:23]
	v_sub_f32_e32 v18, v18, v19
	v_or_b32_e32 v19, 5, v45
	v_cvt_f32_ubyte0_e32 v19, v19
	v_mul_f32_e32 v19, 0xbed49a78, v19
	v_add_f32_e32 v56, v22, v23
	v_exp_f32_e32 v22, v19
	v_mul_f32_e32 v57, 0x3e000000, v18
	v_pk_mul_f32 v[18:19], v[36:37], v[34:35]
	v_add_f32_e32 v42, v42, v43
	v_add_f32_e32 v23, v18, v19
	v_mul_f32_e32 v18, 0.15915494, v22
	v_mul_f32_e32 v19, v18, v44
	v_floor_f32_e32 v19, v19
	v_fma_f32 v19, v18, v44, -v19
	v_cos_f32_e32 v18, v19
	v_sin_f32_e32 v19, v19
	v_mul_f32_e32 v36, 0x3e000000, v23
	v_and_b32_e32 v23, 0xffff0000, v24
	v_and_b32_e32 v22, 0xffff0000, v20
	v_pk_mul_f32 v[34:35], v[18:19], v[22:23]
	v_mul_f32_e32 v43, 0x3e000000, v67
	v_sub_f32_e32 v24, v34, v35
	v_mov_b32_e32 v34, v19
	v_mov_b32_e32 v35, v18
	v_pk_mul_f32 v[18:19], v[18:19], v[32:33]
	v_pk_mul_f32 v[22:23], v[34:35], v[22:23]
	v_sub_f32_e32 v18, v18, v19
	v_or_b32_e32 v19, 6, v45
	v_cvt_f32_ubyte0_e32 v19, v19
	v_mul_f32_e32 v19, 0xbed49a78, v19
	v_exp_f32_e32 v20, v19
	v_mul_f32_e32 v58, 0x3e000000, v18
	v_pk_mul_f32 v[18:19], v[34:35], v[32:33]
	v_add_f32_e32 v37, v22, v23
	v_add_f32_e32 v22, v18, v19
	v_mul_f32_e32 v18, 0.15915494, v20
	v_mul_f32_e32 v19, v18, v44
	v_floor_f32_e32 v19, v19
	v_fma_f32 v19, v18, v44, -v19
	v_cos_f32_e32 v18, v19
	v_sin_f32_e32 v19, v19
	v_mul_f32_e32 v34, 0x3e000000, v22
	v_lshlrev_b32_e32 v23, 16, v25
	v_lshlrev_b32_e32 v22, 16, v21
	v_pk_mul_f32 v[32:33], v[18:19], v[22:23]
	s_nop 0
	v_sub_f32_e32 v35, v32, v33
	v_mov_b32_e32 v32, v19
	v_mov_b32_e32 v33, v18
	v_pk_mul_f32 v[18:19], v[18:19], v[30:31]
	v_pk_mul_f32 v[22:23], v[32:33], v[22:23]
	v_sub_f32_e32 v18, v18, v19
	v_or_b32_e32 v19, 7, v45
	v_cvt_f32_ubyte0_e32 v19, v19
	v_mul_f32_e32 v19, 0xbed49a78, v19
	v_exp_f32_e32 v20, v19
	v_mul_f32_e32 v45, 0x3e000000, v18
	v_pk_mul_f32 v[18:19], v[32:33], v[30:31]
	v_add_f32_e32 v59, v22, v23
	v_add_f32_e32 v22, v18, v19
	v_mul_f32_e32 v18, 0.15915494, v20
	v_mul_f32_e32 v19, v18, v44
	v_floor_f32_e32 v19, v19
	v_fma_f32 v19, v18, v44, -v19
	v_cos_f32_e32 v18, v19
	v_sin_f32_e32 v19, v19
	v_mul_f32_e32 v30, 0x3e000000, v22
	v_and_b32_e32 v23, 0xffff0000, v25
	v_and_b32_e32 v22, 0xffff0000, v21
	v_pk_mul_f32 v[20:21], v[18:19], v[22:23]
	s_nop 0
	v_sub_f32_e32 v25, v20, v21
	v_mov_b32_e32 v20, v19
	v_mov_b32_e32 v21, v18
	v_pk_mul_f32 v[18:19], v[18:19], v[28:29]
	v_pk_mul_f32 v[22:23], v[20:21], v[22:23]
	v_sub_f32_e32 v18, v18, v19
	v_add_f32_e32 v22, v22, v23
	v_mul_f32_e32 v23, 0x3e000000, v18
	v_pk_mul_f32 v[18:19], v[20:21], v[28:29]
	s_nop 0
	v_add_f32_e32 v18, v18, v19
	v_mul_f32_e32 v28, 0x3e000000, v18
	v_cvt_pk_bf16_f32 v18, v50, v39
	v_cvt_pk_bf16_f32 v19, v41, v51
	v_cvt_pk_bf16_f32 v20, v55, v24
	v_cvt_pk_bf16_f32 v21, v35, v25
	global_store_dwordx4 v[26:27], v[18:21], off offset:2880
	s_nop 1
	v_cvt_pk_bf16_f32 v18, v38, v40
	v_cvt_pk_bf16_f32 v19, v42, v52
	v_cvt_pk_bf16_f32 v20, v56, v37
	v_cvt_pk_bf16_f32 v21, v59, v22
	global_store_dwordx4 v[26:27], v[18:21], off offset:2944
	s_nop 1
	v_cvt_pk_bf16_f32 v18, v49, v66
	v_cvt_pk_bf16_f32 v19, v62, v53
	v_cvt_pk_bf16_f32 v20, v57, v58
	v_cvt_pk_bf16_f32 v21, v45, v23
	global_store_dwordx4 v[26:27], v[18:21], off offset:832
	s_nop 1
	v_cvt_pk_bf16_f32 v18, v63, v68
	v_cvt_pk_bf16_f32 v19, v43, v54
	v_cvt_pk_bf16_f32 v20, v36, v34
	v_cvt_pk_bf16_f32 v21, v30, v28
	s_branch .LBB0_605
